# nt (streaming) hint on the read-once bf16 residual-base loads of the P7/P10/P12 epilogues (P2's f32 base loads were nt already)
# baseline (speedup 1.0000x reference)
; __device__ __forceinline__ unsigned cvtpk(float lo, float hi) { f32x2_t v = {lo, hi}; bf16x2_t b = __builtin_convertvector(v, bf16x2_t); return __builtin_bit_cast(unsigned, b); }
; __device__ __forceinline__ float bflo(unsigned w) { return __uint_as_float(w << 16); }
; __device__ __forceinline__ float bfhi(unsigned w) { return __uint_as_float(w & 0xffff0000u); }
;     __device__ __forceinline__ void operator()(const f32x4 (&acc)[2][2][4][2], const Unit& u, int wr, int wc, int fr, int fq) const {
;         const int row0 = u.pm * 256 + wr * 64 + fr, col0 = (u.pn & 7) * 256 + wc * 32 + 8 * fq;
; #pragma unroll
;         for (int ai = 0; ai < 2; ++ai)
; #pragma unroll
;             for (int m = 0; m < 4; ++m) {
;                 const int row = row0 + ai * 128 + m * 16; float s = 0.f;
; #pragma unroll
;                 for (int bj = 0; bj < 2; ++bj) {
;                     const size_t off = (size_t)row * D + col0 + bj * 128;
;                     f32x4 b0, b1;
;                     if (BASE_F32) { b0 = __builtin_nontemporal_load((const f32x4*)(base + off)); b1 = __builtin_nontemporal_load((const f32x4*)(base + off + 4)); }
;                     else { const u32x4 w = *(const u32x4*)(xb + off); b0 = (f32x4){bflo(w.x), bfhi(w.x), bflo(w.y), bfhi(w.y)}; b1 = (f32x4){bflo(w.z), bfhi(w.z), bflo(w.w), bfhi(w.w)}; }
;                     const f32x4 h0 = b0 + acc[ai][bj][m][0] * scale, h1 = b1 + acc[ai][bj][m][1] * scale;
;                     if (OUT_F32) { *(f32x4*)(out + off) = h0; *(f32x4*)(out + off + 4) = h1; }
;                     else { u32x4 w; w.x = cvtpk(h0[0], h0[1]); w.y = cvtpk(h0[2], h0[3]); w.z = cvtpk(h1[0], h1[1]); w.w = cvtpk(h1[2], h1[3]); st16(xb + off, w); }
;                     s += (h0[0] * h0[0] + h0[1] * h0[1]) + (h0[2] * h0[2] + h0[3] * h0[3]) + (h1[0] * h1[0] + h1[1] * h1[1]) + (h1[2] * h1[2] + h1[3] * h1[3]);
;                 }
;                 s += __shfl_xor(s, 16); s += __shfl_xor(s, 32);
;                 if (fq == 0) __hip_atomic_fetch_add(ssq_out + row, s, __ATOMIC_RELAXED, __HIP_MEMORY_SCOPE_AGENT);
.LBB0_1333:
	v_lshl_add_u32 v148, s24, 8, v152
	s_lshl_b32 s17, s26, 8
	s_and_b32 s17, s17, 0x700
	v_ashrrev_i32_e32 v149, 31, v148
	v_or_b32_e32 v138, s17, v154
	v_lshlrev_b64 v[160:161], 12, v[148:149]
	v_lshl_add_u64 v[160:161], s[36:37], 0, v[160:161]
	v_lshlrev_b32_e32 v138, 1, v138
	v_lshl_add_u64 v[170:171], v[160:161], 0, v[138:139]
	global_load_dwordx4 v[162:165], v[170:171], off nt
	global_load_dwordx4 v[166:169], v[170:171], off offset:256 nt
	v_or_b32_e32 v182, 16, v148
	v_ashrrev_i32_e32 v183, 31, v182
	v_lshlrev_b64 v[182:183], 12, v[182:183]
	v_lshl_add_u64 v[182:183], s[36:37], 0, v[182:183]
	v_lshl_add_u64 v[182:183], v[182:183], 0, v[138:139]
	global_load_dwordx4 v[184:187], v[182:183], off nt
	global_load_dwordx4 v[192:195], v[182:183], off offset:256 nt
	v_or_b32_e32 v182, 32, v148
	v_ashrrev_i32_e32 v183, 31, v182
	v_lshlrev_b64 v[182:183], 12, v[182:183]
	v_lshl_add_u64 v[182:183], s[36:37], 0, v[182:183]
	v_lshl_add_u64 v[182:183], v[182:183], 0, v[138:139]
	global_load_dwordx4 v[196:199], v[182:183], off nt
	global_load_dwordx4 v[200:203], v[182:183], off offset:256 nt
	v_or_b32_e32 v182, 48, v148
	v_ashrrev_i32_e32 v183, 31, v182
	v_lshlrev_b64 v[182:183], 12, v[182:183]
	v_lshl_add_u64 v[182:183], s[36:37], 0, v[182:183]
	v_lshl_add_u64 v[182:183], v[182:183], 0, v[138:139]
	global_load_dwordx4 v[204:207], v[182:183], off nt
	global_load_dwordx4 v[208:211], v[182:183], off offset:256 nt
	v_add_u32_e32 v182, 0x80, v148
	v_ashrrev_i32_e32 v183, 31, v182
	v_lshlrev_b64 v[182:183], 12, v[182:183]
	v_lshl_add_u64 v[182:183], s[36:37], 0, v[182:183]
	v_lshl_add_u64 v[182:183], v[182:183], 0, v[138:139]
	global_load_dwordx4 v[212:215], v[182:183], off nt
	global_load_dwordx4 v[216:219], v[182:183], off offset:256 nt
	v_add_u32_e32 v182, 0x90, v148
	v_ashrrev_i32_e32 v183, 31, v182
	v_lshlrev_b64 v[182:183], 12, v[182:183]
	v_lshl_add_u64 v[182:183], s[36:37], 0, v[182:183]
	v_lshl_add_u64 v[182:183], v[182:183], 0, v[138:139]
	global_load_dwordx4 v[220:223], v[182:183], off nt
	global_load_dwordx4 v[224:227], v[182:183], off offset:256 nt
	v_add_u32_e32 v182, 0xa0, v148
	v_ashrrev_i32_e32 v183, 31, v182
	v_lshlrev_b64 v[182:183], 12, v[182:183]
	v_lshl_add_u64 v[182:183], s[36:37], 0, v[182:183]
	v_lshl_add_u64 v[182:183], v[182:183], 0, v[138:139]
	global_load_dwordx4 v[228:231], v[182:183], off nt
	global_load_dwordx4 v[232:235], v[182:183], off offset:256 nt
	v_and_b32_e32 v160, 64, v158
	v_xor_b32_e32 v159, 16, v158
	v_add_u32_e32 v160, 64, v160
	v_xor_b32_e32 v161, 32, v158
	v_cmp_lt_i32_e32 vcc, v159, v160
	s_waitcnt vmcnt(12)
	v_lshlrev_b32_e32 v172, 16, v162
	v_cndmask_b32_e32 v159, v158, v159, vcc
	v_cmp_lt_i32_e32 vcc, v161, v160
	v_and_b32_e32 v173, 0xffff0000, v162
	v_lshlrev_b32_e32 v162, 16, v163
	v_and_b32_e32 v163, 0xffff0000, v163
	v_lshlrev_b32_e32 v176, 16, v166
	v_and_b32_e32 v177, 0xffff0000, v166
	v_lshlrev_b32_e32 v166, 16, v167
	v_and_b32_e32 v167, 0xffff0000, v167
	v_cndmask_b32_e32 v161, v158, v161, vcc
	v_lshlrev_b32_e32 v174, 16, v164
	v_and_b32_e32 v175, 0xffff0000, v164
	v_lshlrev_b32_e32 v164, 16, v165
	v_and_b32_e32 v165, 0xffff0000, v165
	v_lshlrev_b32_e32 v180, 16, v168
	v_and_b32_e32 v181, 0xffff0000, v168
	v_lshlrev_b32_e32 v168, 16, v169
	v_and_b32_e32 v169, 0xffff0000, v169
	v_pk_add_f32 v[128:129], v[128:129], v[162:163]
	v_pk_add_f32 v[126:127], v[126:127], v[172:173]
	v_pk_add_f32 v[120:121], v[120:121], v[166:167]
	v_pk_add_f32 v[118:119], v[118:119], v[176:177]
	v_lshlrev_b32_e32 v160, 2, v159
	v_lshlrev_b32_e32 v159, 2, v161
	v_pk_add_f32 v[124:125], v[124:125], v[164:165]
	v_pk_add_f32 v[122:123], v[122:123], v[174:175]
	v_pk_add_f32 v[162:163], v[116:117], v[168:169]
	v_pk_add_f32 v[164:165], v[114:115], v[180:181]
	v_mul_f32_e32 v116, v127, v127
	v_mul_f32_e32 v117, v129, v129
	v_mul_f32_e32 v161, v119, v119
	v_mul_f32_e32 v166, v121, v121
	v_cvt_pk_bf16_f32 v114, v126, v127
	v_mul_f32_e32 v127, v123, v123
	v_mul_f32_e32 v167, v165, v165
	v_fmac_f32_e32 v116, v126, v126
	v_fmac_f32_e32 v117, v128, v128
	v_fmac_f32_e32 v161, v118, v118
	v_fmac_f32_e32 v166, v120, v120
	v_cvt_pk_bf16_f32 v115, v128, v129
	v_mul_f32_e32 v129, v125, v125
	v_mul_f32_e32 v168, v163, v163
	v_fmac_f32_e32 v127, v122, v122
	v_fmac_f32_e32 v167, v164, v164
	v_add_f32_e32 v116, v116, v117
	v_add_f32_e32 v117, v161, v166
	v_fmac_f32_e32 v129, v124, v124
	v_fmac_f32_e32 v168, v162, v162
	v_add_f32_e32 v116, v127, v116
	v_add_f32_e32 v117, v167, v117
	v_add_f32_e32 v116, v129, v116
	v_add_f32_e32 v117, v168, v117
	v_add_f32_e32 v126, v116, v117
	ds_bpermute_b32 v127, v160, v126
	v_cvt_pk_bf16_f32 v116, v122, v123
	v_cvt_pk_bf16_f32 v117, v124, v125
	global_store_dwordx4 v[170:171], v[114:117], off
	s_waitcnt lgkmcnt(0)
	s_nop 0
	v_add_f32_e32 v114, v126, v127
	ds_bpermute_b32 v115, v159, v114
	v_cvt_pk_bf16_f32 v116, v118, v119
	v_cvt_pk_bf16_f32 v117, v120, v121
	v_cvt_pk_bf16_f32 v118, v164, v165
	v_cvt_pk_bf16_f32 v119, v162, v163
	global_store_dwordx4 v[170:171], v[116:119], off offset:256
	s_and_saveexec_b64 s[24:25], s[2:3]
	s_cbranch_execz .LBB0_1335
	v_lshl_add_u64 v[116:117], v[148:149], 2, s[6:7]
	s_waitcnt lgkmcnt(0)
	v_add_f32_e32 v114, v114, v115
	global_atomic_add_f32 v[116:117], v114, off
; __device__ __forceinline__ unsigned cvtpk(float lo, float hi) { f32x2_t v = {lo, hi}; bf16x2_t b = __builtin_convertvector(v, bf16x2_t); return __builtin_bit_cast(unsigned, b); }
; __device__ __forceinline__ float bflo(unsigned w) { return __uint_as_float(w << 16); }
; __device__ __forceinline__ float bfhi(unsigned w) { return __uint_as_float(w & 0xffff0000u); }
;     __device__ __forceinline__ void operator()(const f32x4 (&acc)[2][2][4][2], const Unit& u, int wr, int wc, int fr, int fq) const {
;     ...
;                 const int row = row0 + ai * 128 + m * 16; float s = 0.f;
; #pragma unroll
;                 for (int bj = 0; bj < 2; ++bj) {
;                     const size_t off = (size_t)row * D + col0 + bj * 128;
;                     f32x4 b0, b1;
;                     if (BASE_F32) { b0 = __builtin_nontemporal_load((const f32x4*)(base + off)); b1 = __builtin_nontemporal_load((const f32x4*)(base + off + 4)); }
;                     else { const u32x4 w = *(const u32x4*)(xb + off); b0 = (f32x4){bflo(w.x), bfhi(w.x), bflo(w.y), bfhi(w.y)}; b1 = (f32x4){bflo(w.z), bfhi(w.z), bflo(w.w), bfhi(w.w)}; }
;                     const f32x4 h0 = b0 + acc[ai][bj][m][0] * scale, h1 = b1 + acc[ai][bj][m][1] * scale;
;                     if (OUT_F32) { *(f32x4*)(out + off) = h0; *(f32x4*)(out + off + 4) = h1; }
;                     else { u32x4 w; w.x = cvtpk(h0[0], h0[1]); w.y = cvtpk(h0[2], h0[3]); w.z = cvtpk(h1[0], h1[1]); w.w = cvtpk(h1[2], h1[3]); st16(xb + off, w); }
;                     s += (h0[0] * h0[0] + h0[1] * h0[1]) + (h0[2] * h0[2] + h0[3] * h0[3]) + (h1[0] * h1[0] + h1[1] * h1[1]) + (h1[2] * h1[2] + h1[3] * h1[3]);
;                 }
;                 s += __shfl_xor(s, 16); s += __shfl_xor(s, 32);
;                 if (fq == 0) __hip_atomic_fetch_add(ssq_out + row, s, __ATOMIC_RELAXED, __HIP_MEMORY_SCOPE_AGENT);
.LBB0_1335:
	s_or_b64 exec, exec, s[24:25]
	v_or_b32_e32 v114, 16, v148
	s_waitcnt lgkmcnt(0)
	v_ashrrev_i32_e32 v115, 31, v114
	v_lshlrev_b64 v[116:117], 12, v[114:115]
	v_lshl_add_u64 v[116:117], s[36:37], 0, v[116:117]
	v_lshl_add_u64 v[124:125], v[116:117], 0, v[138:139]
	s_waitcnt vmcnt(13)
	v_lshlrev_b32_e32 v126, 16, v184
	v_and_b32_e32 v127, 0xffff0000, v184
	v_lshlrev_b32_e32 v116, 16, v185
	v_and_b32_e32 v117, 0xffff0000, v185
	s_waitcnt vmcnt(12)
	v_lshlrev_b32_e32 v162, 16, v192
	v_and_b32_e32 v163, 0xffff0000, v192
	v_lshlrev_b32_e32 v120, 16, v193
	v_and_b32_e32 v121, 0xffff0000, v193
	v_lshlrev_b32_e32 v128, 16, v186
	v_and_b32_e32 v129, 0xffff0000, v186
	v_lshlrev_b32_e32 v118, 16, v187
	v_and_b32_e32 v119, 0xffff0000, v187
	v_lshlrev_b32_e32 v164, 16, v194
	v_and_b32_e32 v165, 0xffff0000, v194
	v_lshlrev_b32_e32 v122, 16, v195
	v_and_b32_e32 v123, 0xffff0000, v195
	v_add_u32_e32 v182, 0xb0, v148
	v_ashrrev_i32_e32 v183, 31, v182
	v_lshlrev_b64 v[182:183], 12, v[182:183]
	v_lshl_add_u64 v[182:183], s[36:37], 0, v[182:183]
	v_lshl_add_u64 v[182:183], v[182:183], 0, v[138:139]
	global_load_dwordx4 v[184:187], v[182:183], off nt
	global_load_dwordx4 v[192:195], v[182:183], off offset:256 nt
	v_pk_add_f32 v[112:113], v[112:113], v[116:117]
	v_pk_add_f32 v[110:111], v[110:111], v[126:127]
	v_pk_add_f32 v[104:105], v[104:105], v[120:121]
	v_pk_add_f32 v[102:103], v[102:103], v[162:163]
	v_pk_add_f32 v[108:109], v[108:109], v[118:119]
	v_pk_add_f32 v[106:107], v[106:107], v[128:129]
	v_pk_add_f32 v[116:117], v[100:101], v[122:123]
	v_pk_add_f32 v[118:119], v[98:99], v[164:165]
	v_mul_f32_e32 v100, v111, v111
	v_mul_f32_e32 v101, v113, v113
	v_mul_f32_e32 v120, v103, v103
	v_mul_f32_e32 v121, v105, v105
	v_cvt_pk_bf16_f32 v98, v110, v111
	v_mul_f32_e32 v111, v107, v107
	v_mul_f32_e32 v122, v119, v119
	v_fmac_f32_e32 v100, v110, v110
	v_fmac_f32_e32 v101, v112, v112
	v_fmac_f32_e32 v120, v102, v102
	v_fmac_f32_e32 v121, v104, v104
	v_cvt_pk_bf16_f32 v99, v112, v113
	v_mul_f32_e32 v113, v109, v109
	v_mul_f32_e32 v123, v117, v117
	v_fmac_f32_e32 v111, v106, v106
	v_fmac_f32_e32 v122, v118, v118
	v_add_f32_e32 v100, v100, v101
	v_add_f32_e32 v101, v120, v121
	v_fmac_f32_e32 v113, v108, v108
	v_fmac_f32_e32 v123, v116, v116
	v_add_f32_e32 v100, v111, v100
	v_add_f32_e32 v101, v122, v101
	v_add_f32_e32 v100, v113, v100
	v_add_f32_e32 v101, v123, v101
	v_add_f32_e32 v110, v100, v101
	ds_bpermute_b32 v111, v160, v110
	v_cvt_pk_bf16_f32 v100, v106, v107
	v_cvt_pk_bf16_f32 v101, v108, v109
	global_store_dwordx4 v[124:125], v[98:101], off
	s_waitcnt lgkmcnt(0)
	s_nop 0
	v_add_f32_e32 v98, v110, v111
	ds_bpermute_b32 v99, v159, v98
	v_cvt_pk_bf16_f32 v100, v102, v103
	v_cvt_pk_bf16_f32 v101, v104, v105
	v_cvt_pk_bf16_f32 v102, v118, v119
	v_cvt_pk_bf16_f32 v103, v116, v117
	global_store_dwordx4 v[124:125], v[100:103], off offset:256
	s_and_saveexec_b64 s[24:25], s[2:3]
	s_cbranch_execz .LBB0_1337
	v_lshl_add_u64 v[100:101], v[114:115], 2, s[6:7]
	s_waitcnt lgkmcnt(0)
	v_add_f32_e32 v98, v98, v99
	global_atomic_add_f32 v[100:101], v98, off

; __device__ __forceinline__ unsigned cvtpk(float lo, float hi) { f32x2_t v = {lo, hi}; bf16x2_t b = __builtin_convertvector(v, bf16x2_t); return __builtin_bit_cast(unsigned, b); }
; __device__ __forceinline__ float bflo(unsigned w) { return __uint_as_float(w << 16); }
; __device__ __forceinline__ float bfhi(unsigned w) { return __uint_as_float(w & 0xffff0000u); }
;     __device__ __forceinline__ void operator()(const f32x4 (&acc)[2][2][4][2], const Unit& u, int wr, int wc, int fr, int fq) const {
;         const int row0 = u.pm * 256 + wr * 64 + fr, col0 = (u.pn & 7) * 256 + wc * 32 + 8 * fq;
; #pragma unroll
;         for (int ai = 0; ai < 2; ++ai)
; #pragma unroll
;             for (int m = 0; m < 4; ++m) {
;                 const int row = row0 + ai * 128 + m * 16; float s = 0.f;
; #pragma unroll
;                 for (int bj = 0; bj < 2; ++bj) {
;                     const size_t off = (size_t)row * D + col0 + bj * 128;
;                     f32x4 b0, b1;
;                     if (BASE_F32) { b0 = __builtin_nontemporal_load((const f32x4*)(base + off)); b1 = __builtin_nontemporal_load((const f32x4*)(base + off + 4)); }
;                     else { const u32x4 w = *(const u32x4*)(xb + off); b0 = (f32x4){bflo(w.x), bfhi(w.x), bflo(w.y), bfhi(w.y)}; b1 = (f32x4){bflo(w.z), bfhi(w.z), bflo(w.w), bfhi(w.w)}; }
;                     const f32x4 h0 = b0 + acc[ai][bj][m][0] * scale, h1 = b1 + acc[ai][bj][m][1] * scale;
;                     if (OUT_F32) { *(f32x4*)(out + off) = h0; *(f32x4*)(out + off + 4) = h1; }
;                     else { u32x4 w; w.x = cvtpk(h0[0], h0[1]); w.y = cvtpk(h0[2], h0[3]); w.z = cvtpk(h1[0], h1[1]); w.w = cvtpk(h1[2], h1[3]); st16(xb + off, w); }
;                     s += (h0[0] * h0[0] + h0[1] * h0[1]) + (h0[2] * h0[2] + h0[3] * h0[3]) + (h1[0] * h1[0] + h1[1] * h1[1]) + (h1[2] * h1[2] + h1[3] * h1[3]);
;                 }
;                 s += __shfl_xor(s, 16); s += __shfl_xor(s, 32);
;                 if (fq == 0) __hip_atomic_fetch_add(ssq_out + row, s, __ATOMIC_RELAXED, __HIP_MEMORY_SCOPE_AGENT);
.LBB0_1607:
	v_lshl_add_u32 v148, s24, 8, v150
	s_lshl_b32 s17, s26, 8
	s_and_b32 s17, s17, 0x700
	v_ashrrev_i32_e32 v149, 31, v148
	v_or_b32_e32 v138, s17, v152
	v_lshlrev_b64 v[158:159], 12, v[148:149]
	v_lshl_add_u64 v[158:159], s[36:37], 0, v[158:159]
	v_lshlrev_b32_e32 v138, 1, v138
	v_lshl_add_u64 v[168:169], v[158:159], 0, v[138:139]
	global_load_dwordx4 v[160:163], v[168:169], off nt
	global_load_dwordx4 v[164:167], v[168:169], off offset:256 nt
	v_or_b32_e32 v178, 16, v148
	v_ashrrev_i32_e32 v179, 31, v178
	v_lshlrev_b64 v[178:179], 12, v[178:179]
	v_lshl_add_u64 v[178:179], s[36:37], 0, v[178:179]
	v_lshl_add_u64 v[178:179], v[178:179], 0, v[138:139]
	global_load_dwordx4 v[180:183], v[178:179], off nt
	global_load_dwordx4 v[184:187], v[178:179], off offset:256 nt
	v_or_b32_e32 v178, 32, v148
	v_ashrrev_i32_e32 v179, 31, v178
	v_lshlrev_b64 v[178:179], 12, v[178:179]
	v_lshl_add_u64 v[178:179], s[36:37], 0, v[178:179]
	v_lshl_add_u64 v[178:179], v[178:179], 0, v[138:139]
	global_load_dwordx4 v[192:195], v[178:179], off nt
	global_load_dwordx4 v[196:199], v[178:179], off offset:256 nt
	v_or_b32_e32 v178, 48, v148
	v_ashrrev_i32_e32 v179, 31, v178
	v_lshlrev_b64 v[178:179], 12, v[178:179]
	v_lshl_add_u64 v[178:179], s[36:37], 0, v[178:179]
	v_lshl_add_u64 v[178:179], v[178:179], 0, v[138:139]
	global_load_dwordx4 v[200:203], v[178:179], off nt
	global_load_dwordx4 v[204:207], v[178:179], off offset:256 nt
	v_add_u32_e32 v178, 0x80, v148
	v_ashrrev_i32_e32 v179, 31, v178
	v_lshlrev_b64 v[178:179], 12, v[178:179]
	v_lshl_add_u64 v[178:179], s[36:37], 0, v[178:179]
	v_lshl_add_u64 v[178:179], v[178:179], 0, v[138:139]
	global_load_dwordx4 v[208:211], v[178:179], off nt
	global_load_dwordx4 v[212:215], v[178:179], off offset:256 nt
	v_add_u32_e32 v178, 0x90, v148
	v_ashrrev_i32_e32 v179, 31, v178
	v_lshlrev_b64 v[178:179], 12, v[178:179]
	v_lshl_add_u64 v[178:179], s[36:37], 0, v[178:179]
	v_lshl_add_u64 v[178:179], v[178:179], 0, v[138:139]
	global_load_dwordx4 v[216:219], v[178:179], off nt
	global_load_dwordx4 v[220:223], v[178:179], off offset:256 nt
	v_add_u32_e32 v178, 0xa0, v148
	v_ashrrev_i32_e32 v179, 31, v178
	v_lshlrev_b64 v[178:179], 12, v[178:179]
	v_lshl_add_u64 v[178:179], s[36:37], 0, v[178:179]
	v_lshl_add_u64 v[178:179], v[178:179], 0, v[138:139]
	global_load_dwordx4 v[224:227], v[178:179], off nt
	global_load_dwordx4 v[228:231], v[178:179], off offset:256 nt
	v_and_b32_e32 v158, 64, v156
	v_xor_b32_e32 v157, 16, v156
	v_add_u32_e32 v158, 64, v158
	v_xor_b32_e32 v159, 32, v156
	v_cmp_lt_i32_e32 vcc, v157, v158
	s_waitcnt vmcnt(12)
	v_lshlrev_b32_e32 v170, 16, v160
	v_cndmask_b32_e32 v157, v156, v157, vcc
	v_cmp_lt_i32_e32 vcc, v159, v158
	v_and_b32_e32 v171, 0xffff0000, v160
	v_lshlrev_b32_e32 v160, 16, v161
	v_and_b32_e32 v161, 0xffff0000, v161
	v_lshlrev_b32_e32 v174, 16, v164
	v_and_b32_e32 v175, 0xffff0000, v164
	v_lshlrev_b32_e32 v164, 16, v165
	v_and_b32_e32 v165, 0xffff0000, v165
	v_cndmask_b32_e32 v159, v156, v159, vcc
	v_lshlrev_b32_e32 v172, 16, v162
	v_and_b32_e32 v173, 0xffff0000, v162
	v_lshlrev_b32_e32 v162, 16, v163
	v_and_b32_e32 v163, 0xffff0000, v163
	v_lshlrev_b32_e32 v176, 16, v166
	v_and_b32_e32 v177, 0xffff0000, v166
	v_lshlrev_b32_e32 v166, 16, v167
	v_and_b32_e32 v167, 0xffff0000, v167
	v_pk_add_f32 v[128:129], v[128:129], v[160:161]
	v_pk_add_f32 v[126:127], v[126:127], v[170:171]
	v_pk_add_f32 v[120:121], v[120:121], v[164:165]
	v_pk_add_f32 v[118:119], v[118:119], v[174:175]
	v_lshlrev_b32_e32 v158, 2, v157
	v_lshlrev_b32_e32 v157, 2, v159
	v_pk_add_f32 v[124:125], v[124:125], v[162:163]
	v_pk_add_f32 v[122:123], v[122:123], v[172:173]
	v_pk_add_f32 v[160:161], v[116:117], v[166:167]
	v_pk_add_f32 v[162:163], v[114:115], v[176:177]
	v_mul_f32_e32 v116, v127, v127
	v_mul_f32_e32 v117, v129, v129
	v_mul_f32_e32 v159, v119, v119
	v_mul_f32_e32 v164, v121, v121
	v_cvt_pk_bf16_f32 v114, v126, v127
	v_mul_f32_e32 v127, v123, v123
	v_mul_f32_e32 v165, v163, v163
	v_fmac_f32_e32 v116, v126, v126
	v_fmac_f32_e32 v117, v128, v128
	v_fmac_f32_e32 v159, v118, v118
	v_fmac_f32_e32 v164, v120, v120
	v_cvt_pk_bf16_f32 v115, v128, v129
	v_mul_f32_e32 v129, v125, v125
	v_mul_f32_e32 v166, v161, v161
	v_fmac_f32_e32 v127, v122, v122
	v_fmac_f32_e32 v165, v162, v162
	v_add_f32_e32 v116, v116, v117
	v_add_f32_e32 v117, v159, v164
	v_fmac_f32_e32 v129, v124, v124
	v_fmac_f32_e32 v166, v160, v160
	v_add_f32_e32 v116, v127, v116
	v_add_f32_e32 v117, v165, v117
	v_add_f32_e32 v116, v129, v116
	v_add_f32_e32 v117, v166, v117
	v_add_f32_e32 v126, v116, v117
	ds_bpermute_b32 v127, v158, v126
	v_cvt_pk_bf16_f32 v116, v122, v123
	v_cvt_pk_bf16_f32 v117, v124, v125
	global_store_dwordx4 v[168:169], v[114:117], off
	s_waitcnt lgkmcnt(0)
	s_nop 0
	v_add_f32_e32 v114, v126, v127
	ds_bpermute_b32 v115, v157, v114
	v_cvt_pk_bf16_f32 v116, v118, v119
	v_cvt_pk_bf16_f32 v117, v120, v121
	v_cvt_pk_bf16_f32 v118, v162, v163
	v_cvt_pk_bf16_f32 v119, v160, v161
	global_store_dwordx4 v[168:169], v[116:119], off offset:256
	s_and_saveexec_b64 s[24:25], s[2:3]
	s_cbranch_execz .LBB0_1609
	v_lshl_add_u64 v[116:117], v[148:149], 2, s[6:7]
	s_waitcnt lgkmcnt(0)
	v_add_f32_e32 v114, v114, v115
	global_atomic_add_f32 v[116:117], v114, off
; __device__ __forceinline__ unsigned cvtpk(float lo, float hi) { f32x2_t v = {lo, hi}; bf16x2_t b = __builtin_convertvector(v, bf16x2_t); return __builtin_bit_cast(unsigned, b); }
; __device__ __forceinline__ float bflo(unsigned w) { return __uint_as_float(w << 16); }
; __device__ __forceinline__ float bfhi(unsigned w) { return __uint_as_float(w & 0xffff0000u); }
;     __device__ __forceinline__ void operator()(const f32x4 (&acc)[2][2][4][2], const Unit& u, int wr, int wc, int fr, int fq) const {
;     ...
;                 const int row = row0 + ai * 128 + m * 16; float s = 0.f;
; #pragma unroll
;                 for (int bj = 0; bj < 2; ++bj) {
;                     const size_t off = (size_t)row * D + col0 + bj * 128;
;                     f32x4 b0, b1;
;                     if (BASE_F32) { b0 = __builtin_nontemporal_load((const f32x4*)(base + off)); b1 = __builtin_nontemporal_load((const f32x4*)(base + off + 4)); }
;                     else { const u32x4 w = *(const u32x4*)(xb + off); b0 = (f32x4){bflo(w.x), bfhi(w.x), bflo(w.y), bfhi(w.y)}; b1 = (f32x4){bflo(w.z), bfhi(w.z), bflo(w.w), bfhi(w.w)}; }
;                     const f32x4 h0 = b0 + acc[ai][bj][m][0] * scale, h1 = b1 + acc[ai][bj][m][1] * scale;
;                     if (OUT_F32) { *(f32x4*)(out + off) = h0; *(f32x4*)(out + off + 4) = h1; }
;                     else { u32x4 w; w.x = cvtpk(h0[0], h0[1]); w.y = cvtpk(h0[2], h0[3]); w.z = cvtpk(h1[0], h1[1]); w.w = cvtpk(h1[2], h1[3]); st16(xb + off, w); }
;                     s += (h0[0] * h0[0] + h0[1] * h0[1]) + (h0[2] * h0[2] + h0[3] * h0[3]) + (h1[0] * h1[0] + h1[1] * h1[1]) + (h1[2] * h1[2] + h1[3] * h1[3]);
;                 }
;                 s += __shfl_xor(s, 16); s += __shfl_xor(s, 32);
;                 if (fq == 0) __hip_atomic_fetch_add(ssq_out + row, s, __ATOMIC_RELAXED, __HIP_MEMORY_SCOPE_AGENT);
.LBB0_1609:
	s_or_b64 exec, exec, s[24:25]
	v_or_b32_e32 v114, 16, v148
	s_waitcnt lgkmcnt(0)
	v_ashrrev_i32_e32 v115, 31, v114
	v_lshlrev_b64 v[116:117], 12, v[114:115]
	v_lshl_add_u64 v[116:117], s[36:37], 0, v[116:117]
	v_lshl_add_u64 v[124:125], v[116:117], 0, v[138:139]
	s_waitcnt vmcnt(13)
	v_lshlrev_b32_e32 v126, 16, v180
	v_and_b32_e32 v127, 0xffff0000, v180
	v_lshlrev_b32_e32 v116, 16, v181
	v_and_b32_e32 v117, 0xffff0000, v181
	s_waitcnt vmcnt(12)
	v_lshlrev_b32_e32 v160, 16, v184
	v_and_b32_e32 v161, 0xffff0000, v184
	v_lshlrev_b32_e32 v120, 16, v185
	v_and_b32_e32 v121, 0xffff0000, v185
	v_lshlrev_b32_e32 v128, 16, v182
	v_and_b32_e32 v129, 0xffff0000, v182
	v_lshlrev_b32_e32 v118, 16, v183
	v_and_b32_e32 v119, 0xffff0000, v183
	v_lshlrev_b32_e32 v162, 16, v186
	v_and_b32_e32 v163, 0xffff0000, v186
	v_lshlrev_b32_e32 v122, 16, v187
	v_and_b32_e32 v123, 0xffff0000, v187
	v_add_u32_e32 v178, 0xb0, v148
	v_ashrrev_i32_e32 v179, 31, v178
	v_lshlrev_b64 v[178:179], 12, v[178:179]
	v_lshl_add_u64 v[178:179], s[36:37], 0, v[178:179]
	v_lshl_add_u64 v[178:179], v[178:179], 0, v[138:139]
	global_load_dwordx4 v[180:183], v[178:179], off nt
	global_load_dwordx4 v[184:187], v[178:179], off offset:256 nt
	v_pk_add_f32 v[112:113], v[112:113], v[116:117]
	v_pk_add_f32 v[110:111], v[110:111], v[126:127]
	v_pk_add_f32 v[104:105], v[104:105], v[120:121]
	v_pk_add_f32 v[102:103], v[102:103], v[160:161]
	v_pk_add_f32 v[108:109], v[108:109], v[118:119]
	v_pk_add_f32 v[106:107], v[106:107], v[128:129]
	v_pk_add_f32 v[116:117], v[100:101], v[122:123]
	v_pk_add_f32 v[118:119], v[98:99], v[162:163]
	v_mul_f32_e32 v100, v111, v111
	v_mul_f32_e32 v101, v113, v113
	v_mul_f32_e32 v120, v103, v103
	v_mul_f32_e32 v121, v105, v105
	v_cvt_pk_bf16_f32 v98, v110, v111
	v_mul_f32_e32 v111, v107, v107
	v_mul_f32_e32 v122, v119, v119
	v_fmac_f32_e32 v100, v110, v110
	v_fmac_f32_e32 v101, v112, v112
	v_fmac_f32_e32 v120, v102, v102
	v_fmac_f32_e32 v121, v104, v104
	v_cvt_pk_bf16_f32 v99, v112, v113
	v_mul_f32_e32 v113, v109, v109
	v_mul_f32_e32 v123, v117, v117
	v_fmac_f32_e32 v111, v106, v106
	v_fmac_f32_e32 v122, v118, v118
	v_add_f32_e32 v100, v100, v101
	v_add_f32_e32 v101, v120, v121
	v_fmac_f32_e32 v113, v108, v108
	v_fmac_f32_e32 v123, v116, v116
	v_add_f32_e32 v100, v111, v100
	v_add_f32_e32 v101, v122, v101
	v_add_f32_e32 v100, v113, v100
	v_add_f32_e32 v101, v123, v101
	v_add_f32_e32 v110, v100, v101
	ds_bpermute_b32 v111, v158, v110
	v_cvt_pk_bf16_f32 v100, v106, v107
	v_cvt_pk_bf16_f32 v101, v108, v109
	global_store_dwordx4 v[124:125], v[98:101], off
	s_waitcnt lgkmcnt(0)
	s_nop 0
	v_add_f32_e32 v98, v110, v111
	ds_bpermute_b32 v99, v157, v98
	v_cvt_pk_bf16_f32 v100, v102, v103
	v_cvt_pk_bf16_f32 v101, v104, v105
	v_cvt_pk_bf16_f32 v102, v118, v119
	v_cvt_pk_bf16_f32 v103, v116, v117
	global_store_dwordx4 v[124:125], v[100:103], off offset:256
	s_and_saveexec_b64 s[24:25], s[2:3]
	s_cbranch_execz .LBB0_1611
	v_lshl_add_u64 v[100:101], v[114:115], 2, s[6:7]
	s_waitcnt lgkmcnt(0)
	v_add_f32_e32 v98, v98, v99
	global_atomic_add_f32 v[100:101], v98, off

; __device__ __forceinline__ float bflo(unsigned w) { return __uint_as_float(w << 16); }
; __device__ __forceinline__ float bfhi(unsigned w) { return __uint_as_float(w & 0xffff0000u); }
;     __device__ __forceinline__ void fused(f32x4 (&acc)[2][2][4][2], const Unit& u, int wr, int wc, int fr, int fq, PG8_LAS unsigned char* lds, int wid, int lane) const {
;     ...
;         const int col0 = u.pn * 256 + wc * 32 + 8 * fq;
; #pragma unroll
;         for (int ai = 0; ai < 2; ++ai)
; #pragma unroll
;             for (int m = 0; m < 4; ++m) {
;                 const int rl = ai * 128 + wr * 64 + m * 16 + fr; float s = 0.f;
; #pragma unroll
;                 for (int bj = 0; bj < 2; ++bj) {
;                     const size_t off = (size_t)(u.pm * 256 + rl) * D + col0 + bj * 128;
;                     const u32x4 w = *(const u32x4*)(xb + off);
;                     const f32x4 b0 = (f32x4){bflo(w.x), bfhi(w.x), bflo(w.y), bfhi(w.y)}, b1 = (f32x4){bflo(w.z), bfhi(w.z), bflo(w.w), bfhi(w.w)};
;                     const f32x4 h0 = b0 + acc[ai][bj][m][0] * scale, h1 = b1 + acc[ai][bj][m][1] * scale;
;                     acc[ai][bj][m][0] = h0; acc[ai][bj][m][1] = h1;
;                     s += (h0[0] * h0[0] + h0[1] * h0[1]) + (h0[2] * h0[2] + h0[3] * h0[3]) + (h1[0] * h1[0] + h1[1] * h1[1]) + (h1[2] * h1[2] + h1[3] * h1[3]);
;                 }
;                 s += __shfl_xor(s, 16); s += __shfl_xor(s, 32);
;                 if (fq == 0) P[rl * 4 + wc] = s;
.LBB0_1911:
	s_lshl_b32 s4, s27, 8
	s_lshl_b32 s0, s29, 5
	s_lshl_b32 s1, s10, 8
	v_add_u32_e32 v130, s4, v164
	s_or_b32 s0, s1, s0
	v_ashrrev_i32_e32 v131, 31, v130
	v_and_or_b32 v132, v150, 24, s0
	v_lshlrev_b64 v[134:135], 12, v[130:131]
	v_ashrrev_i32_e32 v133, 31, v132
	v_lshl_add_u64 v[134:135], s[36:37], 0, v[134:135]
	v_lshl_add_u64 v[138:139], v[132:133], 1, v[134:135]
	s_barrier
	v_mov_b64_e32 v[188:189], v[138:139]
	global_load_dwordx4 v[192:195], v[188:189], off nt
	global_load_dwordx4 v[196:199], v[188:189], off offset:256 nt
	s_mov_b64 s[100:101], 0x10000
	v_lshl_add_u64 v[228:229], v[188:189], 0, s[100:101]
	global_load_dwordx4 v[200:203], v[228:229], off nt
	global_load_dwordx4 v[204:207], v[228:229], off offset:256 nt
	s_mov_b64 s[100:101], 0x20000
	v_lshl_add_u64 v[228:229], v[188:189], 0, s[100:101]
	global_load_dwordx4 v[208:211], v[228:229], off nt
	global_load_dwordx4 v[212:215], v[228:229], off offset:256 nt
	s_mov_b64 s[100:101], 0x30000
	v_lshl_add_u64 v[228:229], v[188:189], 0, s[100:101]
	global_load_dwordx4 v[216:219], v[228:229], off nt
	global_load_dwordx4 v[220:223], v[228:229], off offset:256 nt
	s_nop 0
	v_mbcnt_lo_u32_b32 v142, -1, 0
	v_mbcnt_hi_u32_b32 v150, -1, v142
	v_and_b32_e32 v143, 64, v150
	v_xor_b32_e32 v142, 16, v150
	v_add_u32_e32 v151, 64, v143
	v_cmp_lt_i32_e32 vcc, v142, v151
	s_lshl_b32 s0, s29, 2
	s_add_i32 s2, s0, 0
	v_cndmask_b32_e32 v142, v150, v142, vcc
	v_lshlrev_b32_e32 v165, 2, v142
	s_waitcnt vmcnt(6)
	v_lshlrev_b32_e32 v142, 16, v192
	v_and_b32_e32 v143, 0xffff0000, v192
	v_lshlrev_b32_e32 v134, 16, v193
	v_and_b32_e32 v135, 0xffff0000, v193
	v_lshlrev_b32_e32 v146, 16, v196
	v_and_b32_e32 v147, 0xffff0000, v196
	v_lshlrev_b32_e32 v138, 16, v197
	v_and_b32_e32 v139, 0xffff0000, v197
	v_lshlrev_b32_e32 v144, 16, v194
	v_and_b32_e32 v145, 0xffff0000, v194
	v_lshlrev_b32_e32 v148, 16, v198
	v_and_b32_e32 v149, 0xffff0000, v198
	v_pk_fma_f32 v[128:129], v[128:129], 0.5, v[134:135] op_sel_hi:[1,0,1]
	v_pk_fma_f32 v[126:127], v[126:127], 0.5, v[142:143] op_sel_hi:[1,0,1]
	v_pk_fma_f32 v[120:121], v[120:121], 0.5, v[138:139] op_sel_hi:[1,0,1]
	v_pk_fma_f32 v[118:119], v[118:119], 0.5, v[146:147] op_sel_hi:[1,0,1]
	v_lshlrev_b32_e32 v136, 16, v195
	v_and_b32_e32 v137, 0xffff0000, v195
	v_lshlrev_b32_e32 v140, 16, v199
	v_and_b32_e32 v141, 0xffff0000, v199
	s_mov_b64 s[100:101], 0x80000
	v_lshl_add_u64 v[228:229], v[188:189], 0, s[100:101]
	global_load_dwordx4 v[192:195], v[228:229], off nt
	global_load_dwordx4 v[196:199], v[228:229], off offset:256 nt
	v_pk_fma_f32 v[122:123], v[122:123], 0.5, v[144:145] op_sel_hi:[1,0,1]
	v_pk_fma_f32 v[114:115], v[114:115], 0.5, v[148:149] op_sel_hi:[1,0,1]
	v_mul_f32_e32 v134, v127, v127
	v_mul_f32_e32 v135, v129, v129
	v_mul_f32_e32 v138, v119, v119
	v_mul_f32_e32 v139, v121, v121
	v_pk_fma_f32 v[124:125], v[124:125], 0.5, v[136:137] op_sel_hi:[1,0,1]
	v_pk_fma_f32 v[116:117], v[116:117], 0.5, v[140:141] op_sel_hi:[1,0,1]
	v_mul_f32_e32 v136, v123, v123
	v_mul_f32_e32 v140, v115, v115
	v_fmac_f32_e32 v134, v126, v126
	v_fmac_f32_e32 v135, v128, v128
	v_fmac_f32_e32 v138, v118, v118
	v_fmac_f32_e32 v139, v120, v120
	v_mul_f32_e32 v137, v125, v125
	v_mul_f32_e32 v141, v117, v117
	v_fmac_f32_e32 v136, v122, v122
	v_fmac_f32_e32 v140, v114, v114
	v_add_f32_e32 v134, v134, v135
	v_add_f32_e32 v135, v138, v139
	v_fmac_f32_e32 v137, v124, v124
	v_fmac_f32_e32 v141, v116, v116
	v_add_f32_e32 v134, v136, v134
	v_add_f32_e32 v135, v140, v135
	v_add_f32_e32 v134, v137, v134
	v_add_f32_e32 v135, v141, v135
	v_add_f32_e32 v134, v134, v135
	ds_bpermute_b32 v135, v165, v134
	v_xor_b32_e32 v136, 32, v150
	v_cmp_lt_i32_e32 vcc, v136, v151
	s_waitcnt lgkmcnt(0)
	v_add_f32_e32 v134, v134, v135
	v_cndmask_b32_e32 v136, v150, v136, vcc
	v_lshlrev_b32_e32 v166, 2, v136
	ds_bpermute_b32 v135, v166, v134
	v_cmp_gt_u32_e32 vcc, 16, v190
	s_and_saveexec_b64 s[0:1], vcc
	s_cbranch_execz .LBB0_1913
	v_lshl_add_u32 v136, v164, 4, s2
	s_waitcnt lgkmcnt(0)
	v_add_f32_e32 v134, v134, v135
	ds_write_b32 v136, v134
.LBB0_1913:
	s_or_b64 exec, exec, s[0:1]
	v_or_b32_e32 v136, 16, v164
	v_add_u32_e32 v134, s4, v136
	s_waitcnt lgkmcnt(0)
	v_ashrrev_i32_e32 v135, 31, v134
	v_lshlrev_b64 v[138:139], 12, v[134:135]
	v_lshl_add_u64 v[138:139], s[36:37], 0, v[138:139]
	v_lshl_add_u64 v[142:143], v[132:133], 1, v[138:139]
	s_nop 0
	s_waitcnt vmcnt(7)
	v_lshlrev_b32_e32 v146, 16, v200
	v_and_b32_e32 v147, 0xffff0000, v200
	v_lshlrev_b32_e32 v138, 16, v201
	v_and_b32_e32 v139, 0xffff0000, v201
	s_waitcnt vmcnt(6)
	v_lshlrev_b32_e32 v150, 16, v204
	v_and_b32_e32 v151, 0xffff0000, v204
	v_lshlrev_b32_e32 v142, 16, v205
	v_and_b32_e32 v143, 0xffff0000, v205
	v_lshlrev_b32_e32 v148, 16, v202
	v_and_b32_e32 v149, 0xffff0000, v202
	v_lshlrev_b32_e32 v140, 16, v203
	v_and_b32_e32 v141, 0xffff0000, v203
	v_lshlrev_b32_e32 v152, 16, v206
	v_and_b32_e32 v153, 0xffff0000, v206
	v_pk_fma_f32 v[112:113], v[112:113], 0.5, v[138:139] op_sel_hi:[1,0,1]
	v_pk_fma_f32 v[110:111], v[110:111], 0.5, v[146:147] op_sel_hi:[1,0,1]
	v_pk_fma_f32 v[104:105], v[104:105], 0.5, v[142:143] op_sel_hi:[1,0,1]
	v_pk_fma_f32 v[102:103], v[102:103], 0.5, v[150:151] op_sel_hi:[1,0,1]
	v_lshlrev_b32_e32 v144, 16, v207
	v_and_b32_e32 v145, 0xffff0000, v207
	s_mov_b64 s[100:101], 0x90000
	v_lshl_add_u64 v[228:229], v[188:189], 0, s[100:101]
	global_load_dwordx4 v[200:203], v[228:229], off nt
	global_load_dwordx4 v[204:207], v[228:229], off offset:256 nt
	v_pk_fma_f32 v[108:109], v[108:109], 0.5, v[140:141] op_sel_hi:[1,0,1]
	v_pk_fma_f32 v[106:107], v[106:107], 0.5, v[148:149] op_sel_hi:[1,0,1]
	v_pk_fma_f32 v[98:99], v[98:99], 0.5, v[152:153] op_sel_hi:[1,0,1]
	v_mul_f32_e32 v137, v111, v111
	v_mul_f32_e32 v138, v113, v113
	v_mul_f32_e32 v141, v103, v103
	v_mul_f32_e32 v142, v105, v105
	v_pk_fma_f32 v[100:101], v[100:101], 0.5, v[144:145] op_sel_hi:[1,0,1]
	v_mul_f32_e32 v139, v107, v107
	v_mul_f32_e32 v143, v99, v99
	v_fmac_f32_e32 v137, v110, v110
	v_fmac_f32_e32 v138, v112, v112
	v_fmac_f32_e32 v141, v102, v102
	v_fmac_f32_e32 v142, v104, v104
	v_mul_f32_e32 v140, v109, v109
	v_mul_f32_e32 v144, v101, v101
	v_fmac_f32_e32 v139, v106, v106
	v_fmac_f32_e32 v143, v98, v98
	v_add_f32_e32 v137, v137, v138
	v_add_f32_e32 v138, v141, v142
	v_fmac_f32_e32 v140, v108, v108
	v_fmac_f32_e32 v144, v100, v100
	v_add_f32_e32 v137, v139, v137
	v_add_f32_e32 v138, v143, v138
	v_add_f32_e32 v137, v140, v137
	v_add_f32_e32 v138, v144, v138
	v_add_f32_e32 v137, v137, v138
	ds_bpermute_b32 v138, v165, v137
	s_waitcnt lgkmcnt(0)
	v_add_f32_e32 v137, v137, v138
	ds_bpermute_b32 v138, v166, v137
	s_and_saveexec_b64 s[0:1], vcc
	s_cbranch_execz .LBB0_1915
	v_lshl_add_u32 v136, v136, 4, s2
	s_waitcnt lgkmcnt(0)
	v_add_f32_e32 v137, v137, v138
	ds_write_b32 v136, v137
; __device__ __forceinline__ float bflo(unsigned w) { return __uint_as_float(w << 16); }
; __device__ __forceinline__ float bfhi(unsigned w) { return __uint_as_float(w & 0xffff0000u); }
;     __device__ __forceinline__ void fused(f32x4 (&acc)[2][2][4][2], const Unit& u, int wr, int wc, int fr, int fq, PG8_LAS unsigned char* lds, int wid, int lane) const {
;     ...
;                 const int rl = ai * 128 + wr * 64 + m * 16 + fr; float s = 0.f;
; #pragma unroll
;                 for (int bj = 0; bj < 2; ++bj) {
;                     const size_t off = (size_t)(u.pm * 256 + rl) * D + col0 + bj * 128;
;                     const u32x4 w = *(const u32x4*)(xb + off);
;                     const f32x4 b0 = (f32x4){bflo(w.x), bfhi(w.x), bflo(w.y), bfhi(w.y)}, b1 = (f32x4){bflo(w.z), bfhi(w.z), bflo(w.w), bfhi(w.w)};
;                     const f32x4 h0 = b0 + acc[ai][bj][m][0] * scale, h1 = b1 + acc[ai][bj][m][1] * scale;
;                     acc[ai][bj][m][0] = h0; acc[ai][bj][m][1] = h1;
;                     s += (h0[0] * h0[0] + h0[1] * h0[1]) + (h0[2] * h0[2] + h0[3] * h0[3]) + (h1[0] * h1[0] + h1[1] * h1[1]) + (h1[2] * h1[2] + h1[3] * h1[3]);
;                 }
;                 s += __shfl_xor(s, 16); s += __shfl_xor(s, 32);
;                 if (fq == 0) P[rl * 4 + wc] = s;
.LBB0_1915:
	s_or_b64 exec, exec, s[0:1]
	v_or_b32_e32 v140, 32, v164
	v_add_u32_e32 v136, s4, v140
	v_ashrrev_i32_e32 v137, 31, v136
	s_waitcnt lgkmcnt(0)
	v_lshlrev_b64 v[138:139], 12, v[136:137]
	v_lshl_add_u64 v[138:139], s[36:37], 0, v[138:139]
	v_lshl_add_u64 v[138:139], v[132:133], 1, v[138:139]
	s_waitcnt vmcnt(7)
	v_lshlrev_b32_e32 v138, 16, v208
	v_and_b32_e32 v139, 0xffff0000, v208
	v_lshlrev_b32_e32 v142, 16, v209
	v_and_b32_e32 v143, 0xffff0000, v209
	v_lshlrev_b32_e32 v150, 16, v210
	v_and_b32_e32 v151, 0xffff0000, v210
	s_waitcnt vmcnt(6)
	v_lshlrev_b32_e32 v152, 16, v212
	v_and_b32_e32 v153, 0xffff0000, v212
	v_lshlrev_b32_e32 v146, 16, v213
	v_and_b32_e32 v147, 0xffff0000, v213
	v_lshlrev_b32_e32 v144, 16, v211
	v_and_b32_e32 v145, 0xffff0000, v211
	v_lshlrev_b32_e32 v154, 16, v214
	v_and_b32_e32 v155, 0xffff0000, v214
	v_pk_fma_f32 v[96:97], v[96:97], 0.5, v[142:143] op_sel_hi:[1,0,1]
	v_pk_fma_f32 v[138:139], v[94:95], 0.5, v[138:139] op_sel_hi:[1,0,1]
	v_pk_fma_f32 v[94:95], v[90:91], 0.5, v[150:151] op_sel_hi:[1,0,1]
	v_pk_fma_f32 v[88:89], v[88:89], 0.5, v[146:147] op_sel_hi:[1,0,1]
	v_pk_fma_f32 v[90:91], v[86:87], 0.5, v[152:153] op_sel_hi:[1,0,1]
	v_lshlrev_b32_e32 v148, 16, v215
	v_and_b32_e32 v149, 0xffff0000, v215
	s_mov_b64 s[100:101], 0xa0000
	v_lshl_add_u64 v[228:229], v[188:189], 0, s[100:101]
	global_load_dwordx4 v[208:211], v[228:229], off nt
	global_load_dwordx4 v[212:215], v[228:229], off offset:256 nt
	v_pk_fma_f32 v[92:93], v[92:93], 0.5, v[144:145] op_sel_hi:[1,0,1]
	v_pk_fma_f32 v[86:87], v[82:83], 0.5, v[154:155] op_sel_hi:[1,0,1]
	v_mul_f32_e32 v82, v139, v139
	v_mul_f32_e32 v83, v97, v97
	v_mul_f32_e32 v143, v91, v91
	v_mul_f32_e32 v144, v89, v89
	v_pk_fma_f32 v[84:85], v[84:85], 0.5, v[148:149] op_sel_hi:[1,0,1]
	v_mul_f32_e32 v141, v95, v95
	v_mul_f32_e32 v145, v87, v87
	v_fmac_f32_e32 v82, v138, v138
	v_fmac_f32_e32 v83, v96, v96
	v_fmac_f32_e32 v143, v90, v90
	v_fmac_f32_e32 v144, v88, v88
	v_mul_f32_e32 v142, v93, v93
	v_mul_f32_e32 v146, v85, v85
	v_fmac_f32_e32 v141, v94, v94
	v_fmac_f32_e32 v145, v86, v86
	v_add_f32_e32 v82, v82, v83
	v_add_f32_e32 v83, v143, v144
	v_fmac_f32_e32 v142, v92, v92
	v_fmac_f32_e32 v146, v84, v84
	v_add_f32_e32 v82, v141, v82
	v_add_f32_e32 v83, v145, v83
	v_add_f32_e32 v82, v142, v82
	v_add_f32_e32 v83, v146, v83
	v_add_f32_e32 v82, v82, v83
	ds_bpermute_b32 v83, v165, v82
	s_waitcnt lgkmcnt(0)
	v_add_f32_e32 v82, v82, v83
	ds_bpermute_b32 v83, v166, v82
	s_and_saveexec_b64 s[0:1], vcc
	s_cbranch_execz .LBB0_1917
	v_lshl_add_u32 v140, v140, 4, s2
	s_waitcnt lgkmcnt(0)
	v_add_f32_e32 v82, v82, v83
	ds_write_b32 v140, v82
.LBB0_1917:
	s_or_b64 exec, exec, s[0:1]
	v_or_b32_e32 v140, 48, v164
	v_add_u32_e32 v82, s4, v140
	s_waitcnt lgkmcnt(0)
	v_ashrrev_i32_e32 v83, 31, v82
	v_lshlrev_b64 v[142:143], 12, v[82:83]
	v_lshl_add_u64 v[142:143], s[36:37], 0, v[142:143]
	v_lshl_add_u64 v[146:147], v[132:133], 1, v[142:143]
	s_nop 0
	s_waitcnt vmcnt(7)
	v_lshlrev_b32_e32 v150, 16, v216
	v_and_b32_e32 v151, 0xffff0000, v216
	v_lshlrev_b32_e32 v142, 16, v217
	v_and_b32_e32 v143, 0xffff0000, v217
	s_waitcnt vmcnt(6)
	v_lshlrev_b32_e32 v154, 16, v220
	v_and_b32_e32 v155, 0xffff0000, v220
	v_lshlrev_b32_e32 v146, 16, v221
	v_and_b32_e32 v147, 0xffff0000, v221
	v_lshlrev_b32_e32 v152, 16, v218
	v_and_b32_e32 v153, 0xffff0000, v218
	v_lshlrev_b32_e32 v144, 16, v219
	v_and_b32_e32 v145, 0xffff0000, v219
	v_lshlrev_b32_e32 v156, 16, v222
	v_and_b32_e32 v157, 0xffff0000, v222
	v_pk_fma_f32 v[80:81], v[80:81], 0.5, v[142:143] op_sel_hi:[1,0,1]
	v_pk_fma_f32 v[78:79], v[78:79], 0.5, v[150:151] op_sel_hi:[1,0,1]
	v_pk_fma_f32 v[72:73], v[72:73], 0.5, v[146:147] op_sel_hi:[1,0,1]
	v_pk_fma_f32 v[70:71], v[70:71], 0.5, v[154:155] op_sel_hi:[1,0,1]
	v_lshlrev_b32_e32 v148, 16, v223
	v_and_b32_e32 v149, 0xffff0000, v223
	s_mov_b64 s[100:101], 0xb0000
	v_lshl_add_u64 v[228:229], v[188:189], 0, s[100:101]
	global_load_dwordx4 v[216:219], v[228:229], off nt
	global_load_dwordx4 v[220:223], v[228:229], off offset:256 nt
	v_pk_fma_f32 v[76:77], v[76:77], 0.5, v[144:145] op_sel_hi:[1,0,1]
	v_pk_fma_f32 v[74:75], v[74:75], 0.5, v[152:153] op_sel_hi:[1,0,1]
	v_pk_fma_f32 v[66:67], v[66:67], 0.5, v[156:157] op_sel_hi:[1,0,1]
	v_mul_f32_e32 v141, v79, v79
	v_mul_f32_e32 v142, v81, v81
	v_mul_f32_e32 v145, v71, v71
	v_mul_f32_e32 v146, v73, v73
	v_pk_fma_f32 v[68:69], v[68:69], 0.5, v[148:149] op_sel_hi:[1,0,1]
	v_mul_f32_e32 v143, v75, v75
	v_mul_f32_e32 v147, v67, v67
	v_fmac_f32_e32 v141, v78, v78
	v_fmac_f32_e32 v142, v80, v80
	v_fmac_f32_e32 v145, v70, v70
	v_fmac_f32_e32 v146, v72, v72
	v_mul_f32_e32 v144, v77, v77
	v_mul_f32_e32 v148, v69, v69
	v_fmac_f32_e32 v143, v74, v74
	v_fmac_f32_e32 v147, v66, v66
	v_add_f32_e32 v141, v141, v142
	v_add_f32_e32 v142, v145, v146
	v_fmac_f32_e32 v144, v76, v76
	v_fmac_f32_e32 v148, v68, v68
	v_add_f32_e32 v141, v143, v141
	v_add_f32_e32 v142, v147, v142
	v_add_f32_e32 v141, v144, v141
	v_add_f32_e32 v142, v148, v142
	v_add_f32_e32 v141, v141, v142
	ds_bpermute_b32 v142, v165, v141
	s_waitcnt lgkmcnt(0)
	v_add_f32_e32 v141, v141, v142
	ds_bpermute_b32 v142, v166, v141
	s_and_saveexec_b64 s[0:1], vcc
	s_cbranch_execz .LBB0_1919
	v_lshl_add_u32 v140, v140, 4, s2
	s_waitcnt lgkmcnt(0)
	v_add_f32_e32 v141, v141, v142
	ds_write_b32 v140, v141
